# w_in GEMM epilogue fast path extended to tile column 3 (c_q half + c_kv half, separate row sums / atomics)
# baseline (speedup 1.0000x reference)
.LBB0_295:
	s_cmp_gt_i32 s4, 3
	s_cbranch_scc1 .Lwin_slow
	v_and_b32_e32 v177, 15, v192
	v_bfe_u32 v162, v192, 6, 2
	v_bfe_u32 v163, v192, 4, 2
	v_ashrrev_i32_e32 v80, 2, v192
	v_and_b32_e32 v80, 0xffffffc0, v80
	v_lshl_or_b32 v164, s52, 8, v177
	v_add_u32_e32 v164, v164, v80
	v_ashrrev_i32_e32 v165, 31, v164
	v_lshl_add_u64 v[166:167], v[164:165], 2, s[90:91]
	s_mov_b64 vcc, 0x20000
	s_nop 0
	v_lshl_add_u64 v[166:167], v[166:167], 0, vcc
	global_load_dword v214, v[166:167], off
	global_load_dword v215, v[166:167], off offset:64
	global_load_dword v216, v[166:167], off offset:128
	global_load_dword v217, v[166:167], off offset:192
	global_load_dword v218, v[166:167], off offset:512
	global_load_dword v219, v[166:167], off offset:576
	global_load_dword v220, v[166:167], off offset:640
	global_load_dword v221, v[166:167], off offset:704
	s_lshl_b32 s43, s4, 8
	v_lshlrev_b32_e32 v168, 5, v162
	v_lshlrev_b32_e32 v169, 3, v163
	v_or3_b32 v168, v168, s43, v169
	s_cmp_eq_u32 s4, 2
	s_cbranch_scc1 .Lwin_q
	s_cmp_eq_u32 s4, 3
	s_cbranch_scc1 .Lwin_qk
	v_ashrrev_i32_e32 v170, 4, v168
	v_lshlrev_b32_e32 v170, 10, v170
	v_ashrrev_i32_e32 v171, 5, v164
	v_add_u32_e32 v170, v170, v171
	v_mul_u32_u24_e32 v170, 0x500, v170
	v_lshlrev_b32_e32 v171, 5, v177
	v_and_b32_e32 v169, 8, v169
	v_lshlrev_b32_e32 v169, 1, v169
	v_add3_u32 v170, v170, v171, v169
	v_mov_b32_e32 v171, v81
	v_lshl_add_u64 v[170:171], v[170:171], 0, s[62:63]
	s_mov_b64 vcc, 0x1400
	s_nop 0
	v_lshl_add_u64 v[172:173], v[170:171], 0, vcc
	s_mov_b64 vcc, 0xa00000
	s_nop 0
	v_lshl_add_u64 v[174:175], v[170:171], 0, vcc
	v_lshl_add_u64 v[178:179], v[172:173], 0, vcc
	s_waitcnt vmcnt(7)
	v_fmamk_f32 v180, v214, 0x3a800000, v194
	v_rsq_f32_e32 v180, v180
	s_nop 0
	v_pk_mul_f32 v[126:127], v[126:127], v[180:181] op_sel_hi:[1,0]
	v_pk_mul_f32 v[128:129], v[128:129], v[180:181] op_sel_hi:[1,0]
	v_pk_mul_f32 v[122:123], v[122:123], v[180:181] op_sel_hi:[1,0]
	v_pk_mul_f32 v[124:125], v[124:125], v[180:181] op_sel_hi:[1,0]
	v_cvt_pk_bf16_f32 v126, v126, v127
	v_cvt_pk_bf16_f32 v127, v128, v129
	v_cvt_pk_bf16_f32 v128, v122, v123
	v_cvt_pk_bf16_f32 v129, v124, v125
	global_store_dwordx4 v[170:171], v[126:129], off
	v_pk_mul_f32 v[118:119], v[118:119], v[180:181] op_sel_hi:[1,0]
	v_pk_mul_f32 v[120:121], v[120:121], v[180:181] op_sel_hi:[1,0]
	v_pk_mul_f32 v[114:115], v[114:115], v[180:181] op_sel_hi:[1,0]
	v_pk_mul_f32 v[116:117], v[116:117], v[180:181] op_sel_hi:[1,0]
	v_cvt_pk_bf16_f32 v118, v118, v119
	v_cvt_pk_bf16_f32 v119, v120, v121
	v_cvt_pk_bf16_f32 v120, v114, v115
	v_cvt_pk_bf16_f32 v121, v116, v117
	global_store_dwordx4 v[174:175], v[118:121], off
	s_waitcnt vmcnt(8)
	v_fmamk_f32 v180, v215, 0x3a800000, v194
	v_rsq_f32_e32 v180, v180
	s_nop 0
	v_pk_mul_f32 v[110:111], v[110:111], v[180:181] op_sel_hi:[1,0]
	v_pk_mul_f32 v[112:113], v[112:113], v[180:181] op_sel_hi:[1,0]
	v_pk_mul_f32 v[106:107], v[106:107], v[180:181] op_sel_hi:[1,0]
	v_pk_mul_f32 v[108:109], v[108:109], v[180:181] op_sel_hi:[1,0]
	v_cvt_pk_bf16_f32 v110, v110, v111
	v_cvt_pk_bf16_f32 v111, v112, v113
	v_cvt_pk_bf16_f32 v112, v106, v107
	v_cvt_pk_bf16_f32 v113, v108, v109
	global_store_dwordx4 v[170:171], v[110:113], off offset:512
	v_pk_mul_f32 v[102:103], v[102:103], v[180:181] op_sel_hi:[1,0]
	v_pk_mul_f32 v[104:105], v[104:105], v[180:181] op_sel_hi:[1,0]
	v_pk_mul_f32 v[98:99], v[98:99], v[180:181] op_sel_hi:[1,0]
	v_pk_mul_f32 v[100:101], v[100:101], v[180:181] op_sel_hi:[1,0]
	v_cvt_pk_bf16_f32 v102, v102, v103
	v_cvt_pk_bf16_f32 v103, v104, v105
	v_cvt_pk_bf16_f32 v104, v98, v99
	v_cvt_pk_bf16_f32 v105, v100, v101
	global_store_dwordx4 v[174:175], v[102:105], off offset:512
	s_waitcnt vmcnt(9)
	v_fmamk_f32 v180, v216, 0x3a800000, v194
	v_rsq_f32_e32 v180, v180
	s_nop 0
	v_pk_mul_f32 v[94:95], v[94:95], v[180:181] op_sel_hi:[1,0]
	v_pk_mul_f32 v[96:97], v[96:97], v[180:181] op_sel_hi:[1,0]
	v_pk_mul_f32 v[90:91], v[90:91], v[180:181] op_sel_hi:[1,0]
	v_pk_mul_f32 v[92:93], v[92:93], v[180:181] op_sel_hi:[1,0]
	v_cvt_pk_bf16_f32 v94, v94, v95
	v_cvt_pk_bf16_f32 v95, v96, v97
	v_cvt_pk_bf16_f32 v96, v90, v91
	v_cvt_pk_bf16_f32 v97, v92, v93
	global_store_dwordx4 v[170:171], v[94:97], off offset:1280
	v_pk_mul_f32 v[86:87], v[86:87], v[180:181] op_sel_hi:[1,0]
	v_pk_mul_f32 v[88:89], v[88:89], v[180:181] op_sel_hi:[1,0]
	v_pk_mul_f32 v[82:83], v[82:83], v[180:181] op_sel_hi:[1,0]
	v_pk_mul_f32 v[84:85], v[84:85], v[180:181] op_sel_hi:[1,0]
	v_cvt_pk_bf16_f32 v86, v86, v87
	v_cvt_pk_bf16_f32 v87, v88, v89
	v_cvt_pk_bf16_f32 v88, v82, v83
	v_cvt_pk_bf16_f32 v89, v84, v85
	global_store_dwordx4 v[174:175], v[86:89], off offset:1280
	s_waitcnt vmcnt(10)
	v_fmamk_f32 v180, v217, 0x3a800000, v194
	v_rsq_f32_e32 v180, v180
	s_nop 0
	v_pk_mul_f32 v[76:77], v[76:77], v[180:181] op_sel_hi:[1,0]
	v_pk_mul_f32 v[78:79], v[78:79], v[180:181] op_sel_hi:[1,0]
	v_pk_mul_f32 v[72:73], v[72:73], v[180:181] op_sel_hi:[1,0]
	v_pk_mul_f32 v[74:75], v[74:75], v[180:181] op_sel_hi:[1,0]
	v_cvt_pk_bf16_f32 v76, v76, v77
	v_cvt_pk_bf16_f32 v77, v78, v79
	v_cvt_pk_bf16_f32 v78, v72, v73
	v_cvt_pk_bf16_f32 v79, v74, v75
	global_store_dwordx4 v[170:171], v[76:79], off offset:1792
	v_pk_mul_f32 v[68:69], v[68:69], v[180:181] op_sel_hi:[1,0]
	v_pk_mul_f32 v[70:71], v[70:71], v[180:181] op_sel_hi:[1,0]
	v_pk_mul_f32 v[64:65], v[64:65], v[180:181] op_sel_hi:[1,0]
	v_pk_mul_f32 v[66:67], v[66:67], v[180:181] op_sel_hi:[1,0]
	v_cvt_pk_bf16_f32 v68, v68, v69
	v_cvt_pk_bf16_f32 v69, v70, v71
	v_cvt_pk_bf16_f32 v70, v64, v65
	v_cvt_pk_bf16_f32 v71, v66, v67
	global_store_dwordx4 v[174:175], v[68:71], off offset:1792
	s_waitcnt vmcnt(11)
	v_fmamk_f32 v180, v218, 0x3a800000, v194
	v_rsq_f32_e32 v180, v180
	s_nop 0
	v_pk_mul_f32 v[60:61], v[60:61], v[180:181] op_sel_hi:[1,0]
	v_pk_mul_f32 v[62:63], v[62:63], v[180:181] op_sel_hi:[1,0]
	v_pk_mul_f32 v[56:57], v[56:57], v[180:181] op_sel_hi:[1,0]
	v_pk_mul_f32 v[58:59], v[58:59], v[180:181] op_sel_hi:[1,0]
	v_cvt_pk_bf16_f32 v60, v60, v61
	v_cvt_pk_bf16_f32 v61, v62, v63
	v_cvt_pk_bf16_f32 v62, v56, v57
	v_cvt_pk_bf16_f32 v63, v58, v59
	global_store_dwordx4 v[172:173], v[60:63], off
	v_pk_mul_f32 v[52:53], v[52:53], v[180:181] op_sel_hi:[1,0]
	v_pk_mul_f32 v[54:55], v[54:55], v[180:181] op_sel_hi:[1,0]
	v_pk_mul_f32 v[48:49], v[48:49], v[180:181] op_sel_hi:[1,0]
	v_pk_mul_f32 v[50:51], v[50:51], v[180:181] op_sel_hi:[1,0]
	v_cvt_pk_bf16_f32 v52, v52, v53
	v_cvt_pk_bf16_f32 v53, v54, v55
	v_cvt_pk_bf16_f32 v54, v48, v49
	v_cvt_pk_bf16_f32 v55, v50, v51
	global_store_dwordx4 v[178:179], v[52:55], off
	s_waitcnt vmcnt(12)
	v_fmamk_f32 v180, v219, 0x3a800000, v194
	v_rsq_f32_e32 v180, v180
	s_nop 0
	v_pk_mul_f32 v[44:45], v[44:45], v[180:181] op_sel_hi:[1,0]
	v_pk_mul_f32 v[46:47], v[46:47], v[180:181] op_sel_hi:[1,0]
	v_pk_mul_f32 v[40:41], v[40:41], v[180:181] op_sel_hi:[1,0]
	v_pk_mul_f32 v[42:43], v[42:43], v[180:181] op_sel_hi:[1,0]
	v_cvt_pk_bf16_f32 v44, v44, v45
	v_cvt_pk_bf16_f32 v45, v46, v47
	v_cvt_pk_bf16_f32 v46, v40, v41
	v_cvt_pk_bf16_f32 v47, v42, v43
	global_store_dwordx4 v[172:173], v[44:47], off offset:512
	v_pk_mul_f32 v[36:37], v[36:37], v[180:181] op_sel_hi:[1,0]
	v_pk_mul_f32 v[38:39], v[38:39], v[180:181] op_sel_hi:[1,0]
	v_pk_mul_f32 v[32:33], v[32:33], v[180:181] op_sel_hi:[1,0]
	v_pk_mul_f32 v[34:35], v[34:35], v[180:181] op_sel_hi:[1,0]
	v_cvt_pk_bf16_f32 v36, v36, v37
	v_cvt_pk_bf16_f32 v37, v38, v39
	v_cvt_pk_bf16_f32 v38, v32, v33
	v_cvt_pk_bf16_f32 v39, v34, v35
	global_store_dwordx4 v[178:179], v[36:39], off offset:512
	s_waitcnt vmcnt(13)
	v_fmamk_f32 v180, v220, 0x3a800000, v194
	v_rsq_f32_e32 v180, v180
	s_nop 0
	v_pk_mul_f32 v[28:29], v[28:29], v[180:181] op_sel_hi:[1,0]
	v_pk_mul_f32 v[30:31], v[30:31], v[180:181] op_sel_hi:[1,0]
	v_pk_mul_f32 v[24:25], v[24:25], v[180:181] op_sel_hi:[1,0]
	v_pk_mul_f32 v[26:27], v[26:27], v[180:181] op_sel_hi:[1,0]
	v_cvt_pk_bf16_f32 v28, v28, v29
	v_cvt_pk_bf16_f32 v29, v30, v31
	v_cvt_pk_bf16_f32 v30, v24, v25
	v_cvt_pk_bf16_f32 v31, v26, v27
	global_store_dwordx4 v[172:173], v[28:31], off offset:1280
	v_pk_mul_f32 v[20:21], v[20:21], v[180:181] op_sel_hi:[1,0]
	v_pk_mul_f32 v[22:23], v[22:23], v[180:181] op_sel_hi:[1,0]
	v_pk_mul_f32 v[16:17], v[16:17], v[180:181] op_sel_hi:[1,0]
	v_pk_mul_f32 v[18:19], v[18:19], v[180:181] op_sel_hi:[1,0]
	v_cvt_pk_bf16_f32 v20, v20, v21
	v_cvt_pk_bf16_f32 v21, v22, v23
	v_cvt_pk_bf16_f32 v22, v16, v17
	v_cvt_pk_bf16_f32 v23, v18, v19
	global_store_dwordx4 v[178:179], v[20:23], off offset:1280
	s_waitcnt vmcnt(14)
	v_fmamk_f32 v180, v221, 0x3a800000, v194
	v_rsq_f32_e32 v180, v180
	s_nop 0
	v_pk_mul_f32 v[12:13], v[12:13], v[180:181] op_sel_hi:[1,0]
	v_pk_mul_f32 v[14:15], v[14:15], v[180:181] op_sel_hi:[1,0]
	v_pk_mul_f32 v[8:9], v[8:9], v[180:181] op_sel_hi:[1,0]
	v_pk_mul_f32 v[10:11], v[10:11], v[180:181] op_sel_hi:[1,0]
	v_cvt_pk_bf16_f32 v12, v12, v13
	v_cvt_pk_bf16_f32 v13, v14, v15
	v_cvt_pk_bf16_f32 v14, v8, v9
	v_cvt_pk_bf16_f32 v15, v10, v11
	global_store_dwordx4 v[172:173], v[12:15], off offset:1792
	v_pk_mul_f32 v[4:5], v[4:5], v[180:181] op_sel_hi:[1,0]
	v_pk_mul_f32 v[6:7], v[6:7], v[180:181] op_sel_hi:[1,0]
	v_pk_mul_f32 v[0:1], v[0:1], v[180:181] op_sel_hi:[1,0]
	v_pk_mul_f32 v[2:3], v[2:3], v[180:181] op_sel_hi:[1,0]
	v_cvt_pk_bf16_f32 v4, v4, v5
	v_cvt_pk_bf16_f32 v5, v6, v7
	v_cvt_pk_bf16_f32 v6, v0, v1
	v_cvt_pk_bf16_f32 v7, v2, v3
	global_store_dwordx4 v[178:179], v[4:7], off offset:1792
	s_mov_b64 s[48:49], exec
	s_branch .LBB0_612

.Lwin_qk:
	v_mad_i64_i32 v[170:171], s[46:47], v164, s29, 0
	v_lshl_add_u64 v[170:171], s[90:91], 0, v[170:171]
	v_mov_b32_e32 v169, v81
	v_lshl_add_u64 v[170:171], v[168:169], 1, v[170:171]
	s_mov_b64 vcc, 0x1488f000
	s_nop 0
	v_lshl_add_u64 v[170:171], v[170:171], 0, vcc
	v_lshlrev_b64 v[174:175], 9, v[164:165]
	v_lshl_add_u64 v[174:175], s[90:91], 0, v[174:175]
	v_lshl_add_u64 v[174:175], v[168:169], 1, v[174:175]
	s_mov_b64 vcc, 0x1608f000
	s_nop 0
	v_lshl_add_u64 v[174:175], v[174:175], 0, vcc
	v_lshl_add_u64 v[172:173], v[164:165], 2, s[90:91]
	s_mov_b64 vcc, 0x80000
	s_nop 0
	v_lshl_add_u64 v[172:173], v[172:173], 0, vcc
	s_mov_b64 vcc, 0x20000
	s_nop 0
	v_lshl_add_u64 v[178:179], v[172:173], 0, vcc
	v_cmp_eq_u32_e64 s[46:47], 0, v163
	s_waitcnt vmcnt(7)
	v_fmamk_f32 v180, v214, 0x3a800000, v194
	v_rsq_f32_e32 v180, v180
	s_nop 0
	v_pk_mul_f32 v[126:127], v[126:127], v[180:181] op_sel_hi:[1,0]
	v_pk_mul_f32 v[128:129], v[128:129], v[180:181] op_sel_hi:[1,0]
	v_pk_mul_f32 v[122:123], v[122:123], v[180:181] op_sel_hi:[1,0]
	v_pk_mul_f32 v[124:125], v[124:125], v[180:181] op_sel_hi:[1,0]
	v_pk_mul_f32 v[182:183], v[126:127], v[126:127]
	v_pk_fma_f32 v[182:183], v[128:129], v[128:129], v[182:183]
	v_pk_fma_f32 v[182:183], v[122:123], v[122:123], v[182:183]
	v_pk_fma_f32 v[182:183], v[124:125], v[124:125], v[182:183]
	v_cvt_pk_bf16_f32 v126, v126, v127
	v_cvt_pk_bf16_f32 v127, v128, v129
	v_cvt_pk_bf16_f32 v128, v122, v123
	v_cvt_pk_bf16_f32 v129, v124, v125
	global_store_dwordx4 v[170:171], v[126:129], off offset:3072
	v_add_f32_e32 v184, v182, v183
	v_mov_b32_e32 v185, v184
	s_nop 1
	v_permlane32_swap_b32 v185, v184
	s_nop 1
	v_add_f32_e32 v184, v184, v185
	v_mov_b32_e32 v185, v184
	s_nop 1
	v_permlane16_swap_b32 v185, v184
	s_nop 1
	v_add_f32_e32 v184, v184, v185
	s_mov_b64 exec, s[46:47]
	global_atomic_add_f32 v[172:173], v184, off
	s_mov_b64 exec, -1
	v_pk_mul_f32 v[118:119], v[118:119], v[180:181] op_sel_hi:[1,0]
	v_pk_mul_f32 v[120:121], v[120:121], v[180:181] op_sel_hi:[1,0]
	v_pk_mul_f32 v[114:115], v[114:115], v[180:181] op_sel_hi:[1,0]
	v_pk_mul_f32 v[116:117], v[116:117], v[180:181] op_sel_hi:[1,0]
	v_pk_mul_f32 v[182:183], v[118:119], v[118:119]
	v_pk_fma_f32 v[182:183], v[120:121], v[120:121], v[182:183]
	v_pk_fma_f32 v[182:183], v[114:115], v[114:115], v[182:183]
	v_pk_fma_f32 v[182:183], v[116:117], v[116:117], v[182:183]
	v_cvt_pk_bf16_f32 v118, v118, v119
	v_cvt_pk_bf16_f32 v119, v120, v121
	v_cvt_pk_bf16_f32 v120, v114, v115
	v_cvt_pk_bf16_f32 v121, v116, v117
	global_store_dwordx4 v[174:175], v[118:121], off offset:2560
	v_add_f32_e32 v184, v182, v183
	v_mov_b32_e32 v185, v184
	s_nop 1
	v_permlane32_swap_b32 v185, v184
	s_nop 1
	v_add_f32_e32 v184, v184, v185
	v_mov_b32_e32 v185, v184
	s_nop 1
	v_permlane16_swap_b32 v185, v184
	s_nop 1
	v_add_f32_e32 v184, v184, v185
	s_mov_b64 exec, s[46:47]
	global_atomic_add_f32 v[178:179], v184, off
	s_mov_b64 exec, -1
	s_mov_b64 vcc, 0x3000
	s_nop 0
	v_lshl_add_u64 v[170:171], v[170:171], 0, vcc
	s_mov_b64 vcc, 0x2000
	s_nop 0
	v_lshl_add_u64 v[174:175], v[174:175], 0, vcc
	s_waitcnt vmcnt(10)
	v_fmamk_f32 v180, v215, 0x3a800000, v194
	v_rsq_f32_e32 v180, v180
	s_nop 0
	v_pk_mul_f32 v[110:111], v[110:111], v[180:181] op_sel_hi:[1,0]
	v_pk_mul_f32 v[112:113], v[112:113], v[180:181] op_sel_hi:[1,0]
	v_pk_mul_f32 v[106:107], v[106:107], v[180:181] op_sel_hi:[1,0]
	v_pk_mul_f32 v[108:109], v[108:109], v[180:181] op_sel_hi:[1,0]
	v_pk_mul_f32 v[182:183], v[110:111], v[110:111]
	v_pk_fma_f32 v[182:183], v[112:113], v[112:113], v[182:183]
	v_pk_fma_f32 v[182:183], v[106:107], v[106:107], v[182:183]
	v_pk_fma_f32 v[182:183], v[108:109], v[108:109], v[182:183]
	v_cvt_pk_bf16_f32 v110, v110, v111
	v_cvt_pk_bf16_f32 v111, v112, v113
	v_cvt_pk_bf16_f32 v112, v106, v107
	v_cvt_pk_bf16_f32 v113, v108, v109
	global_store_dwordx4 v[170:171], v[110:113], off offset:3072
	v_add_f32_e32 v184, v182, v183
	v_mov_b32_e32 v185, v184
	s_nop 1
	v_permlane32_swap_b32 v185, v184
	s_nop 1
	v_add_f32_e32 v184, v184, v185
	v_mov_b32_e32 v185, v184
	s_nop 1
	v_permlane16_swap_b32 v185, v184
	s_nop 1
	v_add_f32_e32 v184, v184, v185
	s_mov_b64 exec, s[46:47]
	global_atomic_add_f32 v[172:173], v184, off offset:64
	s_mov_b64 exec, -1
	v_pk_mul_f32 v[102:103], v[102:103], v[180:181] op_sel_hi:[1,0]
	v_pk_mul_f32 v[104:105], v[104:105], v[180:181] op_sel_hi:[1,0]
	v_pk_mul_f32 v[98:99], v[98:99], v[180:181] op_sel_hi:[1,0]
	v_pk_mul_f32 v[100:101], v[100:101], v[180:181] op_sel_hi:[1,0]
	v_pk_mul_f32 v[182:183], v[102:103], v[102:103]
	v_pk_fma_f32 v[182:183], v[104:105], v[104:105], v[182:183]
	v_pk_fma_f32 v[182:183], v[98:99], v[98:99], v[182:183]
	v_pk_fma_f32 v[182:183], v[100:101], v[100:101], v[182:183]
	v_cvt_pk_bf16_f32 v102, v102, v103
	v_cvt_pk_bf16_f32 v103, v104, v105
	v_cvt_pk_bf16_f32 v104, v98, v99
	v_cvt_pk_bf16_f32 v105, v100, v101
	global_store_dwordx4 v[174:175], v[102:105], off offset:2560
	v_add_f32_e32 v184, v182, v183
	v_mov_b32_e32 v185, v184
	s_nop 1
	v_permlane32_swap_b32 v185, v184
	s_nop 1
	v_add_f32_e32 v184, v184, v185
	v_mov_b32_e32 v185, v184
	s_nop 1
	v_permlane16_swap_b32 v185, v184
	s_nop 1
	v_add_f32_e32 v184, v184, v185
	s_mov_b64 exec, s[46:47]
	global_atomic_add_f32 v[178:179], v184, off offset:64
	s_mov_b64 exec, -1
	s_mov_b64 vcc, 0x3000
	s_nop 0
	v_lshl_add_u64 v[170:171], v[170:171], 0, vcc
	s_mov_b64 vcc, 0x2000
	s_nop 0
	v_lshl_add_u64 v[174:175], v[174:175], 0, vcc
	s_waitcnt vmcnt(13)
	v_fmamk_f32 v180, v216, 0x3a800000, v194
	v_rsq_f32_e32 v180, v180
	s_nop 0
	v_pk_mul_f32 v[94:95], v[94:95], v[180:181] op_sel_hi:[1,0]
	v_pk_mul_f32 v[96:97], v[96:97], v[180:181] op_sel_hi:[1,0]
	v_pk_mul_f32 v[90:91], v[90:91], v[180:181] op_sel_hi:[1,0]
	v_pk_mul_f32 v[92:93], v[92:93], v[180:181] op_sel_hi:[1,0]
	v_pk_mul_f32 v[182:183], v[94:95], v[94:95]
	v_pk_fma_f32 v[182:183], v[96:97], v[96:97], v[182:183]
	v_pk_fma_f32 v[182:183], v[90:91], v[90:91], v[182:183]
	v_pk_fma_f32 v[182:183], v[92:93], v[92:93], v[182:183]
	v_cvt_pk_bf16_f32 v94, v94, v95
	v_cvt_pk_bf16_f32 v95, v96, v97
	v_cvt_pk_bf16_f32 v96, v90, v91
	v_cvt_pk_bf16_f32 v97, v92, v93
	global_store_dwordx4 v[170:171], v[94:97], off offset:3072
	v_add_f32_e32 v184, v182, v183
	v_mov_b32_e32 v185, v184
	s_nop 1
	v_permlane32_swap_b32 v185, v184
	s_nop 1
	v_add_f32_e32 v184, v184, v185
	v_mov_b32_e32 v185, v184
	s_nop 1
	v_permlane16_swap_b32 v185, v184
	s_nop 1
	v_add_f32_e32 v184, v184, v185
	s_mov_b64 exec, s[46:47]
	global_atomic_add_f32 v[172:173], v184, off offset:128
	s_mov_b64 exec, -1
	v_pk_mul_f32 v[86:87], v[86:87], v[180:181] op_sel_hi:[1,0]
	v_pk_mul_f32 v[88:89], v[88:89], v[180:181] op_sel_hi:[1,0]
	v_pk_mul_f32 v[82:83], v[82:83], v[180:181] op_sel_hi:[1,0]
	v_pk_mul_f32 v[84:85], v[84:85], v[180:181] op_sel_hi:[1,0]
	v_pk_mul_f32 v[182:183], v[86:87], v[86:87]
	v_pk_fma_f32 v[182:183], v[88:89], v[88:89], v[182:183]
	v_pk_fma_f32 v[182:183], v[82:83], v[82:83], v[182:183]
	v_pk_fma_f32 v[182:183], v[84:85], v[84:85], v[182:183]
	v_cvt_pk_bf16_f32 v86, v86, v87
	v_cvt_pk_bf16_f32 v87, v88, v89
	v_cvt_pk_bf16_f32 v88, v82, v83
	v_cvt_pk_bf16_f32 v89, v84, v85
	global_store_dwordx4 v[174:175], v[86:89], off offset:2560
	v_add_f32_e32 v184, v182, v183
	v_mov_b32_e32 v185, v184
	s_nop 1
	v_permlane32_swap_b32 v185, v184
	s_nop 1
	v_add_f32_e32 v184, v184, v185
	v_mov_b32_e32 v185, v184
	s_nop 1
	v_permlane16_swap_b32 v185, v184
	s_nop 1
	v_add_f32_e32 v184, v184, v185
	s_mov_b64 exec, s[46:47]
	global_atomic_add_f32 v[178:179], v184, off offset:128
	s_mov_b64 exec, -1
	s_mov_b64 vcc, 0x3000
	s_nop 0
	v_lshl_add_u64 v[170:171], v[170:171], 0, vcc
	s_mov_b64 vcc, 0x2000
	s_nop 0
	v_lshl_add_u64 v[174:175], v[174:175], 0, vcc
	s_waitcnt vmcnt(16)
	v_fmamk_f32 v180, v217, 0x3a800000, v194
	v_rsq_f32_e32 v180, v180
	s_nop 0
	v_pk_mul_f32 v[76:77], v[76:77], v[180:181] op_sel_hi:[1,0]
	v_pk_mul_f32 v[78:79], v[78:79], v[180:181] op_sel_hi:[1,0]
	v_pk_mul_f32 v[72:73], v[72:73], v[180:181] op_sel_hi:[1,0]
	v_pk_mul_f32 v[74:75], v[74:75], v[180:181] op_sel_hi:[1,0]
	v_pk_mul_f32 v[182:183], v[76:77], v[76:77]
	v_pk_fma_f32 v[182:183], v[78:79], v[78:79], v[182:183]
	v_pk_fma_f32 v[182:183], v[72:73], v[72:73], v[182:183]
	v_pk_fma_f32 v[182:183], v[74:75], v[74:75], v[182:183]
	v_cvt_pk_bf16_f32 v76, v76, v77
	v_cvt_pk_bf16_f32 v77, v78, v79
	v_cvt_pk_bf16_f32 v78, v72, v73
	v_cvt_pk_bf16_f32 v79, v74, v75
	global_store_dwordx4 v[170:171], v[76:79], off offset:3072
	v_add_f32_e32 v184, v182, v183
	v_mov_b32_e32 v185, v184
	s_nop 1
	v_permlane32_swap_b32 v185, v184
	s_nop 1
	v_add_f32_e32 v184, v184, v185
	v_mov_b32_e32 v185, v184
	s_nop 1
	v_permlane16_swap_b32 v185, v184
	s_nop 1
	v_add_f32_e32 v184, v184, v185
	s_mov_b64 exec, s[46:47]
	global_atomic_add_f32 v[172:173], v184, off offset:192
	s_mov_b64 exec, -1
	v_pk_mul_f32 v[68:69], v[68:69], v[180:181] op_sel_hi:[1,0]
	v_pk_mul_f32 v[70:71], v[70:71], v[180:181] op_sel_hi:[1,0]
	v_pk_mul_f32 v[64:65], v[64:65], v[180:181] op_sel_hi:[1,0]
	v_pk_mul_f32 v[66:67], v[66:67], v[180:181] op_sel_hi:[1,0]
	v_pk_mul_f32 v[182:183], v[68:69], v[68:69]
	v_pk_fma_f32 v[182:183], v[70:71], v[70:71], v[182:183]
	v_pk_fma_f32 v[182:183], v[64:65], v[64:65], v[182:183]
	v_pk_fma_f32 v[182:183], v[66:67], v[66:67], v[182:183]
	v_cvt_pk_bf16_f32 v68, v68, v69
	v_cvt_pk_bf16_f32 v69, v70, v71
	v_cvt_pk_bf16_f32 v70, v64, v65
	v_cvt_pk_bf16_f32 v71, v66, v67
	global_store_dwordx4 v[174:175], v[68:71], off offset:2560
	v_add_f32_e32 v184, v182, v183
	v_mov_b32_e32 v185, v184
	s_nop 1
	v_permlane32_swap_b32 v185, v184
	s_nop 1
	v_add_f32_e32 v184, v184, v185
	v_mov_b32_e32 v185, v184
	s_nop 1
	v_permlane16_swap_b32 v185, v184
	s_nop 1
	v_add_f32_e32 v184, v184, v185
	s_mov_b64 exec, s[46:47]
	global_atomic_add_f32 v[178:179], v184, off offset:192
	s_mov_b64 exec, -1
	s_mov_b64 vcc, 0xf000
	s_nop 0
	v_lshl_add_u64 v[170:171], v[170:171], 0, vcc
	s_mov_b64 vcc, 0xa000
	s_nop 0
	v_lshl_add_u64 v[174:175], v[174:175], 0, vcc
	s_waitcnt vmcnt(19)
	v_fmamk_f32 v180, v218, 0x3a800000, v194
	v_rsq_f32_e32 v180, v180
	s_nop 0
	v_pk_mul_f32 v[60:61], v[60:61], v[180:181] op_sel_hi:[1,0]
	v_pk_mul_f32 v[62:63], v[62:63], v[180:181] op_sel_hi:[1,0]
	v_pk_mul_f32 v[56:57], v[56:57], v[180:181] op_sel_hi:[1,0]
	v_pk_mul_f32 v[58:59], v[58:59], v[180:181] op_sel_hi:[1,0]
	v_pk_mul_f32 v[182:183], v[60:61], v[60:61]
	v_pk_fma_f32 v[182:183], v[62:63], v[62:63], v[182:183]
	v_pk_fma_f32 v[182:183], v[56:57], v[56:57], v[182:183]
	v_pk_fma_f32 v[182:183], v[58:59], v[58:59], v[182:183]
	v_cvt_pk_bf16_f32 v60, v60, v61
	v_cvt_pk_bf16_f32 v61, v62, v63
	v_cvt_pk_bf16_f32 v62, v56, v57
	v_cvt_pk_bf16_f32 v63, v58, v59
	global_store_dwordx4 v[170:171], v[60:63], off offset:3072
	v_add_f32_e32 v184, v182, v183
	v_mov_b32_e32 v185, v184
	s_nop 1
	v_permlane32_swap_b32 v185, v184
	s_nop 1
	v_add_f32_e32 v184, v184, v185
	v_mov_b32_e32 v185, v184
	s_nop 1
	v_permlane16_swap_b32 v185, v184
	s_nop 1
	v_add_f32_e32 v184, v184, v185
	s_mov_b64 exec, s[46:47]
	global_atomic_add_f32 v[172:173], v184, off offset:512
	s_mov_b64 exec, -1
	v_pk_mul_f32 v[52:53], v[52:53], v[180:181] op_sel_hi:[1,0]
	v_pk_mul_f32 v[54:55], v[54:55], v[180:181] op_sel_hi:[1,0]
	v_pk_mul_f32 v[48:49], v[48:49], v[180:181] op_sel_hi:[1,0]
	v_pk_mul_f32 v[50:51], v[50:51], v[180:181] op_sel_hi:[1,0]
	v_pk_mul_f32 v[182:183], v[52:53], v[52:53]
	v_pk_fma_f32 v[182:183], v[54:55], v[54:55], v[182:183]
	v_pk_fma_f32 v[182:183], v[48:49], v[48:49], v[182:183]
	v_pk_fma_f32 v[182:183], v[50:51], v[50:51], v[182:183]
	v_cvt_pk_bf16_f32 v52, v52, v53
	v_cvt_pk_bf16_f32 v53, v54, v55
	v_cvt_pk_bf16_f32 v54, v48, v49
	v_cvt_pk_bf16_f32 v55, v50, v51
	global_store_dwordx4 v[174:175], v[52:55], off offset:2560
	v_add_f32_e32 v184, v182, v183
	v_mov_b32_e32 v185, v184
	s_nop 1
	v_permlane32_swap_b32 v185, v184
	s_nop 1
	v_add_f32_e32 v184, v184, v185
	v_mov_b32_e32 v185, v184
	s_nop 1
	v_permlane16_swap_b32 v185, v184
	s_nop 1
	v_add_f32_e32 v184, v184, v185
	s_mov_b64 exec, s[46:47]
	global_atomic_add_f32 v[178:179], v184, off offset:512
	s_mov_b64 exec, -1
	s_mov_b64 vcc, 0x3000
	s_nop 0
	v_lshl_add_u64 v[170:171], v[170:171], 0, vcc
	s_mov_b64 vcc, 0x2000
	s_nop 0
	v_lshl_add_u64 v[174:175], v[174:175], 0, vcc
	s_waitcnt vmcnt(22)
	v_fmamk_f32 v180, v219, 0x3a800000, v194
	v_rsq_f32_e32 v180, v180
	s_nop 0
	v_pk_mul_f32 v[44:45], v[44:45], v[180:181] op_sel_hi:[1,0]
	v_pk_mul_f32 v[46:47], v[46:47], v[180:181] op_sel_hi:[1,0]
	v_pk_mul_f32 v[40:41], v[40:41], v[180:181] op_sel_hi:[1,0]
	v_pk_mul_f32 v[42:43], v[42:43], v[180:181] op_sel_hi:[1,0]
	v_pk_mul_f32 v[182:183], v[44:45], v[44:45]
	v_pk_fma_f32 v[182:183], v[46:47], v[46:47], v[182:183]
	v_pk_fma_f32 v[182:183], v[40:41], v[40:41], v[182:183]
	v_pk_fma_f32 v[182:183], v[42:43], v[42:43], v[182:183]
	v_cvt_pk_bf16_f32 v44, v44, v45
	v_cvt_pk_bf16_f32 v45, v46, v47
	v_cvt_pk_bf16_f32 v46, v40, v41
	v_cvt_pk_bf16_f32 v47, v42, v43
	global_store_dwordx4 v[170:171], v[44:47], off offset:3072
	v_add_f32_e32 v184, v182, v183
	v_mov_b32_e32 v185, v184
	s_nop 1
	v_permlane32_swap_b32 v185, v184
	s_nop 1
	v_add_f32_e32 v184, v184, v185
	v_mov_b32_e32 v185, v184
	s_nop 1
	v_permlane16_swap_b32 v185, v184
	s_nop 1
	v_add_f32_e32 v184, v184, v185
	s_mov_b64 exec, s[46:47]
	global_atomic_add_f32 v[172:173], v184, off offset:576
	s_mov_b64 exec, -1
	v_pk_mul_f32 v[36:37], v[36:37], v[180:181] op_sel_hi:[1,0]
	v_pk_mul_f32 v[38:39], v[38:39], v[180:181] op_sel_hi:[1,0]
	v_pk_mul_f32 v[32:33], v[32:33], v[180:181] op_sel_hi:[1,0]
	v_pk_mul_f32 v[34:35], v[34:35], v[180:181] op_sel_hi:[1,0]
	v_pk_mul_f32 v[182:183], v[36:37], v[36:37]
	v_pk_fma_f32 v[182:183], v[38:39], v[38:39], v[182:183]
	v_pk_fma_f32 v[182:183], v[32:33], v[32:33], v[182:183]
	v_pk_fma_f32 v[182:183], v[34:35], v[34:35], v[182:183]
	v_cvt_pk_bf16_f32 v36, v36, v37
	v_cvt_pk_bf16_f32 v37, v38, v39
	v_cvt_pk_bf16_f32 v38, v32, v33
	v_cvt_pk_bf16_f32 v39, v34, v35
	global_store_dwordx4 v[174:175], v[36:39], off offset:2560
	v_add_f32_e32 v184, v182, v183
	v_mov_b32_e32 v185, v184
	s_nop 1
	v_permlane32_swap_b32 v185, v184
	s_nop 1
	v_add_f32_e32 v184, v184, v185
	v_mov_b32_e32 v185, v184
	s_nop 1
	v_permlane16_swap_b32 v185, v184
	s_nop 1
	v_add_f32_e32 v184, v184, v185
	s_mov_b64 exec, s[46:47]
	global_atomic_add_f32 v[178:179], v184, off offset:576
	s_mov_b64 exec, -1
	s_mov_b64 vcc, 0x3000
	s_nop 0
	v_lshl_add_u64 v[170:171], v[170:171], 0, vcc
	s_mov_b64 vcc, 0x2000
	s_nop 0
	v_lshl_add_u64 v[174:175], v[174:175], 0, vcc
	s_waitcnt vmcnt(25)
	v_fmamk_f32 v180, v220, 0x3a800000, v194
	v_rsq_f32_e32 v180, v180
	s_nop 0
	v_pk_mul_f32 v[28:29], v[28:29], v[180:181] op_sel_hi:[1,0]
	v_pk_mul_f32 v[30:31], v[30:31], v[180:181] op_sel_hi:[1,0]
	v_pk_mul_f32 v[24:25], v[24:25], v[180:181] op_sel_hi:[1,0]
	v_pk_mul_f32 v[26:27], v[26:27], v[180:181] op_sel_hi:[1,0]
	v_pk_mul_f32 v[182:183], v[28:29], v[28:29]
	v_pk_fma_f32 v[182:183], v[30:31], v[30:31], v[182:183]
	v_pk_fma_f32 v[182:183], v[24:25], v[24:25], v[182:183]
	v_pk_fma_f32 v[182:183], v[26:27], v[26:27], v[182:183]
	v_cvt_pk_bf16_f32 v28, v28, v29
	v_cvt_pk_bf16_f32 v29, v30, v31
	v_cvt_pk_bf16_f32 v30, v24, v25
	v_cvt_pk_bf16_f32 v31, v26, v27
	global_store_dwordx4 v[170:171], v[28:31], off offset:3072
	v_add_f32_e32 v184, v182, v183
	v_mov_b32_e32 v185, v184
	s_nop 1
	v_permlane32_swap_b32 v185, v184
	s_nop 1
	v_add_f32_e32 v184, v184, v185
	v_mov_b32_e32 v185, v184
	s_nop 1
	v_permlane16_swap_b32 v185, v184
	s_nop 1
	v_add_f32_e32 v184, v184, v185
	s_mov_b64 exec, s[46:47]
	global_atomic_add_f32 v[172:173], v184, off offset:640
	s_mov_b64 exec, -1
	v_pk_mul_f32 v[20:21], v[20:21], v[180:181] op_sel_hi:[1,0]
	v_pk_mul_f32 v[22:23], v[22:23], v[180:181] op_sel_hi:[1,0]
	v_pk_mul_f32 v[16:17], v[16:17], v[180:181] op_sel_hi:[1,0]
	v_pk_mul_f32 v[18:19], v[18:19], v[180:181] op_sel_hi:[1,0]
	v_pk_mul_f32 v[182:183], v[20:21], v[20:21]
	v_pk_fma_f32 v[182:183], v[22:23], v[22:23], v[182:183]
	v_pk_fma_f32 v[182:183], v[16:17], v[16:17], v[182:183]
	v_pk_fma_f32 v[182:183], v[18:19], v[18:19], v[182:183]
	v_cvt_pk_bf16_f32 v20, v20, v21
	v_cvt_pk_bf16_f32 v21, v22, v23
	v_cvt_pk_bf16_f32 v22, v16, v17
	v_cvt_pk_bf16_f32 v23, v18, v19
	global_store_dwordx4 v[174:175], v[20:23], off offset:2560
	v_add_f32_e32 v184, v182, v183
	v_mov_b32_e32 v185, v184
	s_nop 1
	v_permlane32_swap_b32 v185, v184
	s_nop 1
	v_add_f32_e32 v184, v184, v185
	v_mov_b32_e32 v185, v184
	s_nop 1
	v_permlane16_swap_b32 v185, v184
	s_nop 1
	v_add_f32_e32 v184, v184, v185
	s_mov_b64 exec, s[46:47]
	global_atomic_add_f32 v[178:179], v184, off offset:640
	s_mov_b64 exec, -1
	s_mov_b64 vcc, 0x3000
	s_nop 0
	v_lshl_add_u64 v[170:171], v[170:171], 0, vcc
	s_mov_b64 vcc, 0x2000
	s_nop 0
	v_lshl_add_u64 v[174:175], v[174:175], 0, vcc
	s_waitcnt vmcnt(28)
	v_fmamk_f32 v180, v221, 0x3a800000, v194
	v_rsq_f32_e32 v180, v180
	s_nop 0
	v_pk_mul_f32 v[12:13], v[12:13], v[180:181] op_sel_hi:[1,0]
	v_pk_mul_f32 v[14:15], v[14:15], v[180:181] op_sel_hi:[1,0]
	v_pk_mul_f32 v[8:9], v[8:9], v[180:181] op_sel_hi:[1,0]
	v_pk_mul_f32 v[10:11], v[10:11], v[180:181] op_sel_hi:[1,0]
	v_pk_mul_f32 v[182:183], v[12:13], v[12:13]
	v_pk_fma_f32 v[182:183], v[14:15], v[14:15], v[182:183]
	v_pk_fma_f32 v[182:183], v[8:9], v[8:9], v[182:183]
	v_pk_fma_f32 v[182:183], v[10:11], v[10:11], v[182:183]
	v_cvt_pk_bf16_f32 v12, v12, v13
	v_cvt_pk_bf16_f32 v13, v14, v15
	v_cvt_pk_bf16_f32 v14, v8, v9
	v_cvt_pk_bf16_f32 v15, v10, v11
	global_store_dwordx4 v[170:171], v[12:15], off offset:3072
	v_add_f32_e32 v184, v182, v183
	v_mov_b32_e32 v185, v184
	s_nop 1
	v_permlane32_swap_b32 v185, v184
	s_nop 1
	v_add_f32_e32 v184, v184, v185
	v_mov_b32_e32 v185, v184
	s_nop 1
	v_permlane16_swap_b32 v185, v184
	s_nop 1
	v_add_f32_e32 v184, v184, v185
	s_mov_b64 exec, s[46:47]
	global_atomic_add_f32 v[172:173], v184, off offset:704
	s_mov_b64 exec, -1
	v_pk_mul_f32 v[4:5], v[4:5], v[180:181] op_sel_hi:[1,0]
	v_pk_mul_f32 v[6:7], v[6:7], v[180:181] op_sel_hi:[1,0]
	v_pk_mul_f32 v[0:1], v[0:1], v[180:181] op_sel_hi:[1,0]
	v_pk_mul_f32 v[2:3], v[2:3], v[180:181] op_sel_hi:[1,0]
	v_pk_mul_f32 v[182:183], v[4:5], v[4:5]
	v_pk_fma_f32 v[182:183], v[6:7], v[6:7], v[182:183]
	v_pk_fma_f32 v[182:183], v[0:1], v[0:1], v[182:183]
	v_pk_fma_f32 v[182:183], v[2:3], v[2:3], v[182:183]
	v_cvt_pk_bf16_f32 v4, v4, v5
	v_cvt_pk_bf16_f32 v5, v6, v7
	v_cvt_pk_bf16_f32 v6, v0, v1
	v_cvt_pk_bf16_f32 v7, v2, v3
	global_store_dwordx4 v[174:175], v[4:7], off offset:2560
	v_add_f32_e32 v184, v182, v183
	v_mov_b32_e32 v185, v184
	s_nop 1
	v_permlane32_swap_b32 v185, v184
	s_nop 1
	v_add_f32_e32 v184, v184, v185
	v_mov_b32_e32 v185, v184
	s_nop 1
	v_permlane16_swap_b32 v185, v184
	s_nop 1
	v_add_f32_e32 v184, v184, v185
	s_mov_b64 exec, s[46:47]
	global_atomic_add_f32 v[178:179], v184, off offset:704
	s_mov_b64 exec, -1
	s_mov_b64 s[48:49], exec
	s_branch .LBB0_612
